# grid barrier release: waiting workgroups poll the cross-XCD arrival counter for >= (generation+1)*XCDs (the last leader's arrival itself releases them; no second atomic hop)
# speedup vs baseline: 1.0080x; 1.0080x over previous
; __device__ __forceinline__ unsigned xb_ld(unsigned* p)              { return __hip_atomic_load(p, __ATOMIC_RELAXED, __HIP_MEMORY_SCOPE_AGENT); }
; __device__ __forceinline__ unsigned xb_add(unsigned* p, unsigned v) { return __hip_atomic_fetch_add(p, v, __ATOMIC_RELAXED, __HIP_MEMORY_SCOPE_AGENT); }
; #define XB_SPIN(cond, bar) do { unsigned _sp = 0; while (cond) { __builtin_amdgcn_s_sleep(1); \
;     if ((++_sp & 255u) == 0u) { if (xb_ld(&(bar)[XB_TMO])) break; if (_sp > XB_SPIN_CAP) { atomicAdd(&(bar)[XB_TMO], 1u); break; } } } } while (0)
; __device__ __forceinline__ void xcd_barrier(const XcdBarrier& b) {
;     ...
;         const unsigned old = xb_add(&bar[XB_XSUB(b.x)], 1u);
;         const unsigned gen = old / nloc;
;         if (old + 1u == (gen + 1u) * nloc) {
;             __builtin_amdgcn_fence(__ATOMIC_RELEASE, "agent");
;             asm volatile("s_waitcnt vmcnt(0)" ::: "memory");
;             const unsigned og = xb_add(&bar[XB_TOP], 1u);
;             const unsigned tg = og / nx;
;             if (og + 1u == (tg + 1u) * nx) xb_add(&bar[XB_TOPGEN], 1u);
;             else XB_SPIN(xb_ld(&bar[XB_TOPGEN]) == tg, bar);
;             __builtin_amdgcn_fence(__ATOMIC_ACQUIRE, "agent");
;             xb_add(&bar[XB_XGEN(b.x)], 1u);
;             asm volatile("s_waitcnt vmcnt(0)" ::: "memory");
;         } else {
;             XB_SPIN(xb_ld(&bar[XB_XGEN(b.x)]) == gen, bar);
.LBB0_50:
	s_or_b64 exec, exec, s[8:9]
	v_cvt_f32_u32_e32 v4, v2
	s_waitcnt vmcnt(0)
	v_readfirstlane_b32 s6, v3
	v_sub_u32_e32 v3, 0, v2
	v_rcp_iflag_f32_e32 v4, v4
	v_add_u32_e32 v5, s6, v1
	v_mul_f32_e32 v4, 0x4f7ffffe, v4
	v_cvt_u32_f32_e32 v4, v4
	v_mul_lo_u32 v1, v3, v4
	v_mul_hi_u32 v1, v4, v1
	v_add_u32_e32 v1, v4, v1
	v_mul_hi_u32 v1, v5, v1
	v_mul_lo_u32 v3, v1, v2
	v_sub_u32_e32 v3, v5, v3
	v_add_u32_e32 v4, 1, v1
	v_cmp_ge_u32_e32 vcc, v3, v2
	s_nop 1
	v_cndmask_b32_e32 v1, v1, v4, vcc
	v_sub_u32_e32 v4, v3, v2
	v_cndmask_b32_e32 v3, v3, v4, vcc
	v_add_u32_e32 v4, 1, v1
	v_cmp_ge_u32_e32 vcc, v3, v2
	v_add_u32_e32 v3, 1, v5
	s_nop 0
	v_cndmask_b32_e32 v1, v1, v4, vcc
	v_mul_lo_u32 v4, v2, v1
	v_add_u32_e32 v2, v4, v2
	v_cmp_ne_u32_e32 vcc, v3, v2
	s_and_saveexec_b64 s[6:7], vcc
	s_xor_b64 s[6:7], exec, s[6:7]
	s_cbranch_execz .LBB0_64
	buffer_inv sc1
	s_waitcnt lgkmcnt(0)
	v_add_u32_e32 v1, 1, v1
	v_mul_lo_u32 v1, v1, v0
	s_add_u32 s12, s50, 0xfc3400
	s_addc_u32 s13, s51, 0
	v_mov_b32_e32 v0, 0
	global_load_dword v0, v0, s[12:13] sc1
	s_waitcnt vmcnt(0)
	v_cmp_lt_u32_e32 vcc, v0, v1
	s_and_saveexec_b64 s[8:9], vcc
	s_cbranch_execz .LBB0_63
	s_add_u32 s10, s50, 0xfc0200
	s_addc_u32 s11, s51, 0
	s_mov_b32 s26, 1
	s_mov_b64 s[14:15], 0
	v_mov_b32_e32 v0, 0
	s_branch .LBB0_54

.LBB0_58:
	global_load_dword v2, v0, s[12:13] sc1
	s_add_i32 s26, s26, 1
	s_mov_b64 s[22:23], -1
	s_waitcnt vmcnt(0)
	v_cmp_ge_u32_e32 vcc, v2, v1
	s_orn2_b64 s[20:21], vcc, exec
	s_branch .LBB0_53

; __device__ __forceinline__ unsigned xb_ld(unsigned* p)              { return __hip_atomic_load(p, __ATOMIC_RELAXED, __HIP_MEMORY_SCOPE_AGENT); }
; __device__ __forceinline__ unsigned xb_add(unsigned* p, unsigned v) { return __hip_atomic_fetch_add(p, v, __ATOMIC_RELAXED, __HIP_MEMORY_SCOPE_AGENT); }
; #define XB_SPIN(cond, bar) do { unsigned _sp = 0; while (cond) { __builtin_amdgcn_s_sleep(1); \
;     if ((++_sp & 255u) == 0u) { if (xb_ld(&(bar)[XB_TMO])) break; if (_sp > XB_SPIN_CAP) { atomicAdd(&(bar)[XB_TMO], 1u); break; } } } } while (0)
; __device__ __forceinline__ void xcd_barrier(const XcdBarrier& b) {
;     ...
;         const unsigned old = xb_add(&bar[XB_XSUB(b.x)], 1u);
;         const unsigned gen = old / nloc;
;         if (old + 1u == (gen + 1u) * nloc) {
;             __builtin_amdgcn_fence(__ATOMIC_RELEASE, "agent");
;             asm volatile("s_waitcnt vmcnt(0)" ::: "memory");
;             const unsigned og = xb_add(&bar[XB_TOP], 1u);
;             const unsigned tg = og / nx;
;             if (og + 1u == (tg + 1u) * nx) xb_add(&bar[XB_TOPGEN], 1u);
;             else XB_SPIN(xb_ld(&bar[XB_TOPGEN]) == tg, bar);
;             __builtin_amdgcn_fence(__ATOMIC_ACQUIRE, "agent");
;             xb_add(&bar[XB_XGEN(b.x)], 1u);
;             asm volatile("s_waitcnt vmcnt(0)" ::: "memory");
;         } else {
;             XB_SPIN(xb_ld(&bar[XB_XGEN(b.x)]) == gen, bar);
.LBB0_376:
	s_or_b64 exec, exec, s[8:9]
	v_cvt_f32_u32_e32 v4, v2
	s_waitcnt vmcnt(0)
	v_readfirstlane_b32 s6, v3
	v_sub_u32_e32 v3, 0, v2
	v_rcp_iflag_f32_e32 v4, v4
	v_add_u32_e32 v5, s6, v1
	v_mul_f32_e32 v4, 0x4f7ffffe, v4
	v_cvt_u32_f32_e32 v4, v4
	v_mul_lo_u32 v1, v3, v4
	v_mul_hi_u32 v1, v4, v1
	v_add_u32_e32 v1, v4, v1
	v_mul_hi_u32 v1, v5, v1
	v_mul_lo_u32 v3, v1, v2
	v_sub_u32_e32 v3, v5, v3
	v_add_u32_e32 v4, 1, v1
	v_cmp_ge_u32_e32 vcc, v3, v2
	s_nop 1
	v_cndmask_b32_e32 v1, v1, v4, vcc
	v_sub_u32_e32 v4, v3, v2
	v_cndmask_b32_e32 v3, v3, v4, vcc
	v_add_u32_e32 v4, 1, v1
	v_cmp_ge_u32_e32 vcc, v3, v2
	v_add_u32_e32 v3, 1, v5
	s_nop 0
	v_cndmask_b32_e32 v1, v1, v4, vcc
	v_mul_lo_u32 v4, v2, v1
	v_add_u32_e32 v2, v4, v2
	v_cmp_ne_u32_e32 vcc, v3, v2
	s_and_saveexec_b64 s[6:7], vcc
	s_xor_b64 s[6:7], exec, s[6:7]
	s_cbranch_execz .LBB0_390
	buffer_inv sc1
	s_waitcnt lgkmcnt(0)
	v_add_u32_e32 v1, 1, v1
	v_mul_lo_u32 v1, v1, v0
	s_add_u32 s12, s50, 0xfc3400
	s_addc_u32 s13, s51, 0
	v_mov_b32_e32 v0, 0
	global_load_dword v0, v0, s[12:13] sc1
	s_waitcnt vmcnt(0)
	v_cmp_lt_u32_e32 vcc, v0, v1
	s_and_saveexec_b64 s[8:9], vcc
	s_cbranch_execz .LBB0_389
	s_add_u32 s10, s50, 0xfc0200
	s_addc_u32 s11, s51, 0
	s_mov_b32 s28, 1
	s_mov_b64 s[14:15], 0
	v_mov_b32_e32 v0, 0
	s_branch .LBB0_380

.LBB0_384:
	global_load_dword v2, v0, s[12:13] sc1
	s_add_i32 s28, s28, 1
	s_mov_b64 s[24:25], -1
	s_waitcnt vmcnt(0)
	v_cmp_ge_u32_e32 vcc, v2, v1
	s_orn2_b64 s[22:23], vcc, exec
	s_branch .LBB0_379

; __device__ __forceinline__ unsigned xb_ld(unsigned* p)              { return __hip_atomic_load(p, __ATOMIC_RELAXED, __HIP_MEMORY_SCOPE_AGENT); }
; __device__ __forceinline__ unsigned xb_add(unsigned* p, unsigned v) { return __hip_atomic_fetch_add(p, v, __ATOMIC_RELAXED, __HIP_MEMORY_SCOPE_AGENT); }
; #define XB_SPIN(cond, bar) do { unsigned _sp = 0; while (cond) { __builtin_amdgcn_s_sleep(1); \
;     if ((++_sp & 255u) == 0u) { if (xb_ld(&(bar)[XB_TMO])) break; if (_sp > XB_SPIN_CAP) { atomicAdd(&(bar)[XB_TMO], 1u); break; } } } } while (0)
; __device__ __forceinline__ void xcd_barrier(const XcdBarrier& b) {
;     ...
;         const unsigned old = xb_add(&bar[XB_XSUB(b.x)], 1u);
;         const unsigned gen = old / nloc;
;         if (old + 1u == (gen + 1u) * nloc) {
;             __builtin_amdgcn_fence(__ATOMIC_RELEASE, "agent");
;             asm volatile("s_waitcnt vmcnt(0)" ::: "memory");
;             const unsigned og = xb_add(&bar[XB_TOP], 1u);
;             const unsigned tg = og / nx;
;             if (og + 1u == (tg + 1u) * nx) xb_add(&bar[XB_TOPGEN], 1u);
;             else XB_SPIN(xb_ld(&bar[XB_TOPGEN]) == tg, bar);
;             __builtin_amdgcn_fence(__ATOMIC_ACQUIRE, "agent");
;             xb_add(&bar[XB_XGEN(b.x)], 1u);
;             asm volatile("s_waitcnt vmcnt(0)" ::: "memory");
;         } else {
;             XB_SPIN(xb_ld(&bar[XB_XGEN(b.x)]) == gen, bar);
.LBB0_492:
	s_or_b64 exec, exec, s[8:9]
	v_cvt_f32_u32_e32 v4, v2
	s_waitcnt vmcnt(0)
	v_readfirstlane_b32 s6, v3
	v_sub_u32_e32 v3, 0, v2
	v_rcp_iflag_f32_e32 v4, v4
	v_add_u32_e32 v5, s6, v1
	v_mul_f32_e32 v4, 0x4f7ffffe, v4
	v_cvt_u32_f32_e32 v4, v4
	v_mul_lo_u32 v1, v3, v4
	v_mul_hi_u32 v1, v4, v1
	v_add_u32_e32 v1, v4, v1
	v_mul_hi_u32 v1, v5, v1
	v_mul_lo_u32 v3, v1, v2
	v_sub_u32_e32 v3, v5, v3
	v_add_u32_e32 v4, 1, v1
	v_cmp_ge_u32_e32 vcc, v3, v2
	s_nop 1
	v_cndmask_b32_e32 v1, v1, v4, vcc
	v_sub_u32_e32 v4, v3, v2
	v_cndmask_b32_e32 v3, v3, v4, vcc
	v_add_u32_e32 v4, 1, v1
	v_cmp_ge_u32_e32 vcc, v3, v2
	v_add_u32_e32 v3, 1, v5
	s_nop 0
	v_cndmask_b32_e32 v1, v1, v4, vcc
	v_mul_lo_u32 v4, v2, v1
	v_add_u32_e32 v2, v4, v2
	v_cmp_ne_u32_e32 vcc, v3, v2
	s_and_saveexec_b64 s[6:7], vcc
	s_xor_b64 s[6:7], exec, s[6:7]
	s_cbranch_execz .LBB0_506
	buffer_inv sc1
	s_waitcnt lgkmcnt(0)
	v_add_u32_e32 v1, 1, v1
	v_mul_lo_u32 v1, v1, v0
	s_add_u32 s12, s50, 0xfc3400
	s_addc_u32 s13, s51, 0
	v_mov_b32_e32 v0, 0
	global_load_dword v0, v0, s[12:13] sc1
	s_waitcnt vmcnt(0)
	v_cmp_lt_u32_e32 vcc, v0, v1
	s_and_saveexec_b64 s[8:9], vcc
	s_cbranch_execz .LBB0_505
	s_add_u32 s10, s50, 0xfc0200
	s_addc_u32 s11, s51, 0
	s_mov_b32 s30, 1
	s_mov_b64 s[14:15], 0
	v_mov_b32_e32 v0, 0
	s_branch .LBB0_496

.LBB0_500:
	global_load_dword v2, v0, s[12:13] sc1
	s_add_i32 s30, s30, 1
	s_mov_b64 s[26:27], -1
	s_waitcnt vmcnt(0)
	v_cmp_ge_u32_e32 vcc, v2, v1
	s_orn2_b64 s[24:25], vcc, exec
	s_branch .LBB0_495

; __device__ __forceinline__ unsigned xb_ld(unsigned* p)              { return __hip_atomic_load(p, __ATOMIC_RELAXED, __HIP_MEMORY_SCOPE_AGENT); }
; __device__ __forceinline__ unsigned xb_add(unsigned* p, unsigned v) { return __hip_atomic_fetch_add(p, v, __ATOMIC_RELAXED, __HIP_MEMORY_SCOPE_AGENT); }
; #define XB_SPIN(cond, bar) do { unsigned _sp = 0; while (cond) { __builtin_amdgcn_s_sleep(1); \
;     if ((++_sp & 255u) == 0u) { if (xb_ld(&(bar)[XB_TMO])) break; if (_sp > XB_SPIN_CAP) { atomicAdd(&(bar)[XB_TMO], 1u); break; } } } } while (0)
; __device__ __forceinline__ void xcd_barrier(const XcdBarrier& b) {
;     ...
;         const unsigned old = xb_add(&bar[XB_XSUB(b.x)], 1u);
;         const unsigned gen = old / nloc;
;         if (old + 1u == (gen + 1u) * nloc) {
;             __builtin_amdgcn_fence(__ATOMIC_RELEASE, "agent");
;             asm volatile("s_waitcnt vmcnt(0)" ::: "memory");
;             const unsigned og = xb_add(&bar[XB_TOP], 1u);
;             const unsigned tg = og / nx;
;             if (og + 1u == (tg + 1u) * nx) xb_add(&bar[XB_TOPGEN], 1u);
;             else XB_SPIN(xb_ld(&bar[XB_TOPGEN]) == tg, bar);
;             __builtin_amdgcn_fence(__ATOMIC_ACQUIRE, "agent");
;             xb_add(&bar[XB_XGEN(b.x)], 1u);
;             asm volatile("s_waitcnt vmcnt(0)" ::: "memory");
;         } else {
;             XB_SPIN(xb_ld(&bar[XB_XGEN(b.x)]) == gen, bar);
.LBB0_586:
	s_or_b64 exec, exec, s[14:15]
	v_cvt_f32_u32_e32 v4, v2
	s_waitcnt vmcnt(0)
	v_readfirstlane_b32 s8, v3
	v_sub_u32_e32 v3, 0, v2
	v_rcp_iflag_f32_e32 v4, v4
	v_add_u32_e32 v5, s8, v1
	v_mul_f32_e32 v4, 0x4f7ffffe, v4
	v_cvt_u32_f32_e32 v4, v4
	v_mul_lo_u32 v1, v3, v4
	v_mul_hi_u32 v1, v4, v1
	v_add_u32_e32 v1, v4, v1
	v_mul_hi_u32 v1, v5, v1
	v_mul_lo_u32 v3, v1, v2
	v_sub_u32_e32 v3, v5, v3
	v_add_u32_e32 v4, 1, v1
	v_cmp_ge_u32_e32 vcc, v3, v2
	s_nop 1
	v_cndmask_b32_e32 v1, v1, v4, vcc
	v_sub_u32_e32 v4, v3, v2
	v_cndmask_b32_e32 v3, v3, v4, vcc
	v_add_u32_e32 v4, 1, v1
	v_cmp_ge_u32_e32 vcc, v3, v2
	v_add_u32_e32 v3, 1, v5
	s_nop 0
	v_cndmask_b32_e32 v1, v1, v4, vcc
	v_mul_lo_u32 v4, v2, v1
	v_add_u32_e32 v2, v4, v2
	v_cmp_ne_u32_e32 vcc, v3, v2
	s_and_saveexec_b64 s[8:9], vcc
	s_xor_b64 s[8:9], exec, s[8:9]
	s_cbranch_execz .LBB0_600
	buffer_inv sc1
	s_waitcnt lgkmcnt(0)
	v_add_u32_e32 v1, 1, v1
	v_mul_lo_u32 v1, v1, v0
	s_add_u32 s24, s50, 0xfc3400
	s_addc_u32 s25, s51, 0
	v_mov_b32_e32 v0, 0
	global_load_dword v0, v0, s[24:25] sc1
	s_waitcnt vmcnt(0)
	v_cmp_lt_u32_e32 vcc, v0, v1
	s_and_saveexec_b64 s[14:15], vcc
	s_cbranch_execz .LBB0_599
	s_add_u32 s16, s50, 0xfc0200
	s_addc_u32 s17, s51, 0
	s_mov_b32 s33, 1
	s_mov_b64 s[26:27], 0
	v_mov_b32_e32 v0, 0
	s_branch .LBB0_590

.LBB0_594:
	global_load_dword v2, v0, s[24:25] sc1
	s_add_i32 s33, s33, 1
	s_mov_b64 s[34:35], -1
	s_waitcnt vmcnt(0)
	v_cmp_ge_u32_e32 vcc, v2, v1
	s_orn2_b64 s[30:31], vcc, exec
	s_branch .LBB0_589

; __device__ __forceinline__ unsigned xb_ld(unsigned* p)              { return __hip_atomic_load(p, __ATOMIC_RELAXED, __HIP_MEMORY_SCOPE_AGENT); }
; __device__ __forceinline__ unsigned xb_add(unsigned* p, unsigned v) { return __hip_atomic_fetch_add(p, v, __ATOMIC_RELAXED, __HIP_MEMORY_SCOPE_AGENT); }
; #define XB_SPIN(cond, bar) do { unsigned _sp = 0; while (cond) { __builtin_amdgcn_s_sleep(1); \
;     if ((++_sp & 255u) == 0u) { if (xb_ld(&(bar)[XB_TMO])) break; if (_sp > XB_SPIN_CAP) { atomicAdd(&(bar)[XB_TMO], 1u); break; } } } } while (0)
; __device__ __forceinline__ void xcd_barrier(const XcdBarrier& b) {
;     ...
;         const unsigned old = xb_add(&bar[XB_XSUB(b.x)], 1u);
;         const unsigned gen = old / nloc;
;         if (old + 1u == (gen + 1u) * nloc) {
;             __builtin_amdgcn_fence(__ATOMIC_RELEASE, "agent");
;             asm volatile("s_waitcnt vmcnt(0)" ::: "memory");
;             const unsigned og = xb_add(&bar[XB_TOP], 1u);
;             const unsigned tg = og / nx;
;             if (og + 1u == (tg + 1u) * nx) xb_add(&bar[XB_TOPGEN], 1u);
;             else XB_SPIN(xb_ld(&bar[XB_TOPGEN]) == tg, bar);
;             __builtin_amdgcn_fence(__ATOMIC_ACQUIRE, "agent");
;             xb_add(&bar[XB_XGEN(b.x)], 1u);
;             asm volatile("s_waitcnt vmcnt(0)" ::: "memory");
;         } else {
;             XB_SPIN(xb_ld(&bar[XB_XGEN(b.x)]) == gen, bar);
.LBB0_662:
	s_or_b64 exec, exec, s[14:15]
	v_cvt_f32_u32_e32 v4, v2
	s_waitcnt vmcnt(0)
	v_readfirstlane_b32 s3, v3
	v_sub_u32_e32 v3, 0, v2
	v_rcp_iflag_f32_e32 v4, v4
	v_add_u32_e32 v5, s3, v1
	v_mul_f32_e32 v4, 0x4f7ffffe, v4
	v_cvt_u32_f32_e32 v4, v4
	v_mul_lo_u32 v1, v3, v4
	v_mul_hi_u32 v1, v4, v1
	v_add_u32_e32 v1, v4, v1
	v_mul_hi_u32 v1, v5, v1
	v_mul_lo_u32 v3, v1, v2
	v_sub_u32_e32 v3, v5, v3
	v_add_u32_e32 v4, 1, v1
	v_cmp_ge_u32_e32 vcc, v3, v2
	s_nop 1
	v_cndmask_b32_e32 v1, v1, v4, vcc
	v_sub_u32_e32 v4, v3, v2
	v_cndmask_b32_e32 v3, v3, v4, vcc
	v_add_u32_e32 v4, 1, v1
	v_cmp_ge_u32_e32 vcc, v3, v2
	v_add_u32_e32 v3, 1, v5
	s_nop 0
	v_cndmask_b32_e32 v1, v1, v4, vcc
	v_mul_lo_u32 v4, v2, v1
	v_add_u32_e32 v2, v4, v2
	v_cmp_ne_u32_e32 vcc, v3, v2
	s_and_saveexec_b64 s[8:9], vcc
	s_xor_b64 s[8:9], exec, s[8:9]
	s_cbranch_execz .LBB0_676
	buffer_inv sc1
	s_waitcnt lgkmcnt(0)
	v_add_u32_e32 v1, 1, v1
	v_mul_lo_u32 v1, v1, v0
	s_add_u32 s18, s50, 0xfc3400
	s_addc_u32 s19, s51, 0
	v_mov_b32_e32 v0, 0
	global_load_dword v0, v0, s[18:19] sc1
	s_waitcnt vmcnt(0)
	v_cmp_lt_u32_e32 vcc, v0, v1
	s_and_saveexec_b64 s[14:15], vcc
	s_cbranch_execz .LBB0_675
	s_add_u32 s16, s50, 0xfc0200
	s_addc_u32 s17, s51, 0
	s_mov_b32 s3, 1
	s_mov_b64 s[22:23], 0
	v_mov_b32_e32 v0, 0
	s_branch .LBB0_666

.LBB0_670:
	global_load_dword v2, v0, s[18:19] sc1
	s_add_i32 s3, s3, 1
	s_mov_b64 s[28:29], -1
	s_waitcnt vmcnt(0)
	v_cmp_ge_u32_e32 vcc, v2, v1
	s_orn2_b64 s[26:27], vcc, exec
	s_branch .LBB0_665
